# scalar control-flow trim: step-2 DMA-arrival wait selector collapsed to one branch (no s[54:55] flag round-trip)
# speedup vs baseline: 1.0031x; 1.0031x over previous
; template <bool FIRST> __device__ __forceinline__ void partialSM(f32x16& p0, f32x16& p1, float& m_reg, f32x16& negm, float& alpha) {
;     ...
;   for (int r = 0; r < 16; ++r) p0[r] = __builtin_amdgcn_exp2f(p0[r]);
; }
; __device__ __forceinline__ void finishSM(f32x16& p0, f32x16& p1, float alpha, float& l_reg, bf16x8& pa0, bf16x8& pa1, bf16x8& pa2, bf16x8& pa3) {
; #pragma unroll
;   for (int r = 0; r < 16; ++r) p1[r] = __builtin_amdgcn_exp2f(p1[r]);
;   float ps = 0;
; #pragma unroll
;   for (int r = 0; r < 16; ++r) ps += p0[r];
; #pragma unroll
;   for (int r = 0; r < 16; ++r) ps += p1[r];
;   { auto rr = __builtin_amdgcn_permlane32_swap(__float_as_uint(ps), __float_as_uint(ps), false, false);
;     ps = __uint_as_float(rr[0]) + __uint_as_float(rr[1]); }
;   l_reg = l_reg * alpha + ps;
; __device__ __forceinline__ void unit(const bf16* Qb, const bf16* __restrict__ Kh, const bf16* __restrict__ Vh, bf16* Ob, float lam, float post, const float* __restrict__ gsub, char* lds) {
;     ...
;   int sk = 32768, sv = 0, sw = 98304;
.LBB0_209:
	v_exp_f32_e32 v172, v128
	v_exp_f32_e32 v174, v129
	v_exp_f32_e32 v175, v130
	v_exp_f32_e32 v211, v131
	v_exp_f32_e32 v212, v132
	v_exp_f32_e32 v215, v133
	v_exp_f32_e32 v216, v134
	v_exp_f32_e32 v233, v135
	v_exp_f32_e32 v173, v136
	v_exp_f32_e32 v176, v137
	v_exp_f32_e32 v177, v138
	v_exp_f32_e32 v213, v139
	v_exp_f32_e32 v214, v140
	v_exp_f32_e32 v217, v141
	v_exp_f32_e32 v232, v142
	v_exp_f32_e32 v234, v143
	v_add_f32_e32 v115, v208, v209
	s_add_i32 s44, s44, 2
	s_xor_b32 s39, s39, 0x10000
	s_xor_b32 s56, s56, 0x10000
	v_fmac_f32_e32 v115, v207, v180
	v_add_f32_e32 v180, v113, v114
	s_add_u32 s50, s50, 0x20000
	v_fmac_f32_e32 v180, v115, v210
	s_addc_u32 s51, s51, 0
	v_mov_b32_e32 v207, v112
	s_and_b64 vcc, exec, s[52:53]
	s_cbranch_vccz .LBB0_211
	s_waitcnt vmcnt(0) lgkmcnt(0)
	s_branch .LBB0_213
.LBB0_211:
	s_waitcnt vmcnt(4) lgkmcnt(0)
